# D attention loops: waves 4-7 issue their K/V LDS-DMA pieces between the P.V MFMAs instead of right after the tile barrier
# baseline (speedup 1.0000x reference)
.LBB0_702:
	s_lshl_b32 s20, s35, 14
	s_add_i32 m0, s81, s22
	s_addk_i32 s20, 0xc000
	s_cmp_gt_i32 s35, 0
	s_cselect_b32 s20, s20, 0xc000
	s_waitcnt vmcnt(3) lgkmcnt(0)
	s_barrier
	s_add_i32 s20, s63, s20
	s_branch .Lmy_r2d_0

.Lmy_r2ft_0:
	s_cmpk_gt_u32 s57, 0xfc
	s_mov_b64 s[20:21], -1
	s_cbranch_scc1 .LBB0_746
	s_andn2_b64 vcc, exec, s[20:21]
	s_cbranch_vccnz .LBB0_708

.LBB0_717:
	s_lshl_b32 s22, s35, 14
	s_add_i32 m0, s81, s78
	s_addk_i32 s22, 0xc000
	s_cmp_gt_i32 s35, 0
	s_cselect_b32 s22, s22, 0xc000
	s_waitcnt vmcnt(3) lgkmcnt(0)
	s_barrier
	s_add_i32 s22, s63, s22
	s_branch .Lmy_r2d_1

.Lmy_r2ft_1:
	s_cmpk_gt_u32 s57, 0xfb
	s_mov_b64 s[22:23], -1
	s_cbranch_scc1 .LBB0_756
	s_andn2_b64 vcc, exec, s[22:23]
	s_cbranch_vccnz .LBB0_723

; #define SBAR() __builtin_amdgcn_sched_barrier(0)
; template <int D0> __device__ __forceinline__ void pv_one(f32x16& od, int vb, bf16x8 pa0, bf16x8 pa1, bf16x8 pa2, bf16x8 pa3) {
;     const s16x4 l0 = tr_read<v_rd_off(D0, 0, 0)>(vb), h0 = tr_read<v_rd_off(D0, 0, 1)>(vb), l1 = tr_read<v_rd_off(D0, 1, 0)>(vb), h1 = tr_read<v_rd_off(D0, 1, 1)>(vb);
;     const s16x4 l2 = tr_read<v_rd_off(D0, 2, 0)>(vb), h2 = tr_read<v_rd_off(D0, 2, 1)>(vb), l3 = tr_read<v_rd_off(D0, 3, 0)>(vb), h3 = tr_read<v_rd_off(D0, 3, 1)>(vb);
;     asm volatile("s_waitcnt lgkmcnt(0)" ::: "memory"); SBAR();
;     ...
;     od = __builtin_amdgcn_mfma_f32_32x32x16_bf16(pa0, PK(l0, h0), od, 0, 0, 0);
;     od = __builtin_amdgcn_mfma_f32_32x32x16_bf16(pa1, PK(l1, h1), od, 0, 0, 0);
;     od = __builtin_amdgcn_mfma_f32_32x32x16_bf16(pa2, PK(l2, h2), od, 0, 0, 0);
;     od = __builtin_amdgcn_mfma_f32_32x32x16_bf16(pa3, PK(l3, h3), od, 0, 0, 0);
;     ...
; }
; template <bool RSM> __device__ __forceinline__ void pv_d0(f32x16* o, f32x16& lacc, int vb, bf16x8 pa0, bf16x8 pa1, bf16x8 pa2, bf16x8 pa3) {
;     if (RSM) {
;         const bf16x8 ones = {0x3F80, 0x3F80, 0x3F80, 0x3F80, 0x3F80, 0x3F80, 0x3F80, 0x3F80};
;         lacc = __builtin_amdgcn_mfma_f32_32x32x16_bf16(pa0, ones, lacc, 0, 0, 0);
;         lacc = __builtin_amdgcn_mfma_f32_32x32x16_bf16(pa1, ones, lacc, 0, 0, 0);
;         lacc = __builtin_amdgcn_mfma_f32_32x32x16_bf16(pa2, ones, lacc, 0, 0, 0);
;         lacc = __builtin_amdgcn_mfma_f32_32x32x16_bf16(pa3, ones, lacc, 0, 0, 0); }
;     pv_one<0>(o[0], vb, pa0, pa1, pa2, pa3); pv_one<1>(o[1], vb, pa0, pa1, pa2, pa3); pv_one<2>(o[2], vb, pa0, pa1, pa2, pa3); pv_one<3>(o[3], vb, pa0, pa1, pa2, pa3);
.Lmy_r2d_0:
	s_mov_b32 s38, s36
	s_mov_b32 s39, s36
	s_mov_b32 s37, s36
	v_mov_b64_e32 v[134:135], s[38:39]
	v_mov_b64_e32 v[132:133], s[36:37]
	s_lshl_b32 s23, s35, 14
	v_add_u32_e32 v0, s23, v230
	v_mfma_f32_32x32x16_bf16 v[96:111], v[6:9], v[132:135], v[96:111]
	ds_read_b64_tr_b16 v[136:137], v0 offset:0
	ds_read_b64_tr_b16 v[138:139], v0 offset:0x800
	ds_read_b64_tr_b16 v[140:141], v0 offset:0x1000
	ds_read_b64_tr_b16 v[142:143], v0 offset:0x1800
	ds_read_b64_tr_b16 v[192:193], v0 offset:0x2000
	ds_read_b64_tr_b16 v[194:195], v0 offset:0x2800
	ds_read_b64_tr_b16 v[196:197], v0 offset:0x3000
	v_mfma_f32_32x32x16_bf16 v[96:111], v[2:5], v[132:135], v[96:111]
	global_load_lds_dwordx4 v[214:215], off
	v_lshl_add_u64 v[214:215], v[214:215], 0, s[74:75]
	ds_read_b64_tr_b16 v[198:199], v0 offset:0x3800
	s_waitcnt lgkmcnt(0)
	v_mfma_f32_32x32x16_bf16 v[96:111], v[128:131], v[132:135], v[96:111]
	v_mfma_f32_32x32x16_bf16 v[96:111], v[10:13], v[132:135], v[96:111]
	v_mfma_f32_32x32x16_bf16 v[80:95], v[6:9], v[136:139], v[80:95]
	ds_read_b64_tr_b16 v[132:133], v0 offset:0x200
	ds_read_b64_tr_b16 v[134:135], v0 offset:0xa00
	ds_read_b64_tr_b16 v[136:137], v0 offset:0x1200
	ds_read_b64_tr_b16 v[138:139], v0 offset:0x1a00
	v_mfma_f32_32x32x16_bf16 v[80:95], v[2:5], v[140:143], v[80:95]
	s_mov_b32 m0, s20
	s_nop 0
	global_load_lds_dwordx4 v[212:213], off
	v_lshl_add_u64 v[212:213], v[212:213], 0, s[74:75]
	ds_read_b64_tr_b16 v[140:141], v0 offset:0x2200
	ds_read_b64_tr_b16 v[142:143], v0 offset:0x2a00
	v_mfma_f32_32x32x16_bf16 v[80:95], v[128:131], v[192:195], v[80:95]
	ds_read_b64_tr_b16 v[192:193], v0 offset:0x3200
	ds_read_b64_tr_b16 v[194:195], v0 offset:0x3a00
	s_waitcnt lgkmcnt(0)
	v_mfma_f32_32x32x16_bf16 v[80:95], v[10:13], v[196:199], v[80:95]
	v_mfma_f32_32x32x16_bf16 v[64:79], v[6:9], v[132:135], v[64:79]
	ds_read_b64_tr_b16 v[132:133], v0 offset:0x400
	ds_read_b64_tr_b16 v[134:135], v0 offset:0xc00
	v_mfma_f32_32x32x16_bf16 v[64:79], v[2:5], v[136:139], v[64:79]
	s_add_i32 m0, s20, 0x2000
	s_nop 0
	global_load_lds_dwordx4 v[216:217], off
	v_lshl_add_u64 v[216:217], v[216:217], 0, s[74:75]
	ds_read_b64_tr_b16 v[136:137], v0 offset:0x1400
	ds_read_b64_tr_b16 v[138:139], v0 offset:0x1c00
	v_mfma_f32_32x32x16_bf16 v[64:79], v[128:131], v[140:143], v[64:79]
	ds_read_b64_tr_b16 v[140:141], v0 offset:0x2400
	ds_read_b64_tr_b16 v[142:143], v0 offset:0x2c00
	v_mfma_f32_32x32x16_bf16 v[64:79], v[10:13], v[192:195], v[64:79]
	ds_read_b64_tr_b16 v[192:193], v0 offset:0x3400
	ds_read_b64_tr_b16 v[194:195], v0 offset:0x3c00
	s_waitcnt lgkmcnt(0)
	v_mfma_f32_32x32x16_bf16 v[48:63], v[6:9], v[132:135], v[48:63]
	ds_read_b64_tr_b16 v[132:133], v0 offset:0x600
	ds_read_b64_tr_b16 v[134:135], v0 offset:0xe00
	v_mfma_f32_32x32x16_bf16 v[48:63], v[2:5], v[136:139], v[48:63]
	ds_read_b64_tr_b16 v[136:137], v0 offset:0x1600
	ds_read_b64_tr_b16 v[138:139], v0 offset:0x1e00
	v_mfma_f32_32x32x16_bf16 v[48:63], v[128:131], v[140:143], v[48:63]
	ds_read_b64_tr_b16 v[140:141], v0 offset:0x2600
	ds_read_b64_tr_b16 v[142:143], v0 offset:0x2e00
	v_mfma_f32_32x32x16_bf16 v[48:63], v[10:13], v[192:195], v[48:63]
	ds_read_b64_tr_b16 v[192:193], v0 offset:0x3600
	ds_read_b64_tr_b16 v[194:195], v0 offset:0x3e00
	s_waitcnt lgkmcnt(0)
	v_mfma_f32_32x32x16_bf16 v[32:47], v[6:9], v[132:135], v[32:47]
	s_and_b64 vcc, exec, s[0:1]
	v_mfma_f32_32x32x16_bf16 v[32:47], v[2:5], v[136:139], v[32:47]
	v_mfma_f32_32x32x16_bf16 v[32:47], v[128:131], v[140:143], v[32:47]
	v_mfma_f32_32x32x16_bf16 v[32:47], v[10:13], v[192:195], v[32:47]
	s_cbranch_vccnz .LBB0_709
	s_branch .Lmy_r2ft_0
.Lmy_r2d_1:
	s_mov_b32 s38, s36
	s_mov_b32 s39, s36
	s_mov_b32 s37, s36
	v_mov_b64_e32 v[150:151], s[38:39]
	v_mov_b64_e32 v[148:149], s[36:37]
	s_lshl_b32 s37, s35, 14
	v_add_u32_e32 v14, s37, v230
	v_mfma_f32_32x32x16_bf16 v[96:111], v[6:9], v[148:151], v[96:111]
	ds_read_b64_tr_b16 v[152:153], v14 offset:0
	ds_read_b64_tr_b16 v[154:155], v14 offset:0x800
	ds_read_b64_tr_b16 v[156:157], v14 offset:0x1000
	ds_read_b64_tr_b16 v[158:159], v14 offset:0x1800
	ds_read_b64_tr_b16 v[192:193], v14 offset:0x2000
	ds_read_b64_tr_b16 v[194:195], v14 offset:0x2800
	ds_read_b64_tr_b16 v[196:197], v14 offset:0x3000
	v_mfma_f32_32x32x16_bf16 v[96:111], v[2:5], v[148:151], v[96:111]
	global_load_lds_dwordx4 v[214:215], off
	v_lshl_add_u64 v[214:215], v[214:215], 0, s[74:75]
	ds_read_b64_tr_b16 v[198:199], v14 offset:0x3800
	s_waitcnt lgkmcnt(0)
	v_mfma_f32_32x32x16_bf16 v[96:111], v[144:147], v[148:151], v[96:111]
	v_mfma_f32_32x32x16_bf16 v[96:111], v[10:13], v[148:151], v[96:111]
	v_mfma_f32_32x32x16_bf16 v[80:95], v[6:9], v[152:155], v[80:95]
	ds_read_b64_tr_b16 v[148:149], v14 offset:0x200
	ds_read_b64_tr_b16 v[150:151], v14 offset:0xa00
	ds_read_b64_tr_b16 v[152:153], v14 offset:0x1200
	ds_read_b64_tr_b16 v[154:155], v14 offset:0x1a00
	v_mfma_f32_32x32x16_bf16 v[80:95], v[2:5], v[156:159], v[80:95]
	s_mov_b32 m0, s22
	s_nop 0
	global_load_lds_dwordx4 v[212:213], off
	v_lshl_add_u64 v[212:213], v[212:213], 0, s[74:75]
	ds_read_b64_tr_b16 v[156:157], v14 offset:0x2200
	ds_read_b64_tr_b16 v[158:159], v14 offset:0x2a00
	v_mfma_f32_32x32x16_bf16 v[80:95], v[144:147], v[192:195], v[80:95]
	ds_read_b64_tr_b16 v[192:193], v14 offset:0x3200
	ds_read_b64_tr_b16 v[194:195], v14 offset:0x3a00
	s_waitcnt lgkmcnt(0)
; #define SBAR() __builtin_amdgcn_sched_barrier(0)
; template <int D0> __device__ __forceinline__ void pv_one(f32x16& od, int vb, bf16x8 pa0, bf16x8 pa1, bf16x8 pa2, bf16x8 pa3) {
;     const s16x4 l0 = tr_read<v_rd_off(D0, 0, 0)>(vb), h0 = tr_read<v_rd_off(D0, 0, 1)>(vb), l1 = tr_read<v_rd_off(D0, 1, 0)>(vb), h1 = tr_read<v_rd_off(D0, 1, 1)>(vb);
;     const s16x4 l2 = tr_read<v_rd_off(D0, 2, 0)>(vb), h2 = tr_read<v_rd_off(D0, 2, 1)>(vb), l3 = tr_read<v_rd_off(D0, 3, 0)>(vb), h3 = tr_read<v_rd_off(D0, 3, 1)>(vb);
;     asm volatile("s_waitcnt lgkmcnt(0)" ::: "memory"); SBAR();
;     ...
;     od = __builtin_amdgcn_mfma_f32_32x32x16_bf16(pa0, PK(l0, h0), od, 0, 0, 0);
;     od = __builtin_amdgcn_mfma_f32_32x32x16_bf16(pa1, PK(l1, h1), od, 0, 0, 0);
;     od = __builtin_amdgcn_mfma_f32_32x32x16_bf16(pa2, PK(l2, h2), od, 0, 0, 0);
;     od = __builtin_amdgcn_mfma_f32_32x32x16_bf16(pa3, PK(l3, h3), od, 0, 0, 0);
;     ...
; }
; template <bool RSM> __device__ __forceinline__ void pv_d0(f32x16* o, f32x16& lacc, int vb, bf16x8 pa0, bf16x8 pa1, bf16x8 pa2, bf16x8 pa3) {
;     if (RSM) {
;         const bf16x8 ones = {0x3F80, 0x3F80, 0x3F80, 0x3F80, 0x3F80, 0x3F80, 0x3F80, 0x3F80};
;         lacc = __builtin_amdgcn_mfma_f32_32x32x16_bf16(pa0, ones, lacc, 0, 0, 0);
;         lacc = __builtin_amdgcn_mfma_f32_32x32x16_bf16(pa1, ones, lacc, 0, 0, 0);
;         lacc = __builtin_amdgcn_mfma_f32_32x32x16_bf16(pa2, ones, lacc, 0, 0, 0);
;         lacc = __builtin_amdgcn_mfma_f32_32x32x16_bf16(pa3, ones, lacc, 0, 0, 0); }
;     pv_one<0>(o[0], vb, pa0, pa1, pa2, pa3); pv_one<1>(o[1], vb, pa0, pa1, pa2, pa3); pv_one<2>(o[2], vb, pa0, pa1, pa2, pa3); pv_one<3>(o[3], vb, pa0, pa1, pa2, pa3);
	v_mfma_f32_32x32x16_bf16 v[80:95], v[10:13], v[196:199], v[80:95]
	v_mfma_f32_32x32x16_bf16 v[64:79], v[6:9], v[148:151], v[64:79]
	ds_read_b64_tr_b16 v[148:149], v14 offset:0x400
	ds_read_b64_tr_b16 v[150:151], v14 offset:0xc00
	v_mfma_f32_32x32x16_bf16 v[64:79], v[2:5], v[152:155], v[64:79]
	s_add_i32 m0, s22, 0x2000
	s_nop 0
	global_load_lds_dwordx4 v[216:217], off
	v_lshl_add_u64 v[216:217], v[216:217], 0, s[74:75]
	ds_read_b64_tr_b16 v[152:153], v14 offset:0x1400
	ds_read_b64_tr_b16 v[154:155], v14 offset:0x1c00
	v_mfma_f32_32x32x16_bf16 v[64:79], v[144:147], v[156:159], v[64:79]
	ds_read_b64_tr_b16 v[156:157], v14 offset:0x2400
	ds_read_b64_tr_b16 v[158:159], v14 offset:0x2c00
	v_mfma_f32_32x32x16_bf16 v[64:79], v[10:13], v[192:195], v[64:79]
	ds_read_b64_tr_b16 v[192:193], v14 offset:0x3400
	ds_read_b64_tr_b16 v[194:195], v14 offset:0x3c00
	s_waitcnt lgkmcnt(0)
	v_mfma_f32_32x32x16_bf16 v[48:63], v[6:9], v[148:151], v[48:63]
	ds_read_b64_tr_b16 v[148:149], v14 offset:0x600
	ds_read_b64_tr_b16 v[150:151], v14 offset:0xe00
	v_mfma_f32_32x32x16_bf16 v[48:63], v[2:5], v[152:155], v[48:63]
	ds_read_b64_tr_b16 v[152:153], v14 offset:0x1600
	ds_read_b64_tr_b16 v[154:155], v14 offset:0x1e00
	v_mfma_f32_32x32x16_bf16 v[48:63], v[144:147], v[156:159], v[48:63]
	ds_read_b64_tr_b16 v[156:157], v14 offset:0x2600
	ds_read_b64_tr_b16 v[158:159], v14 offset:0x2e00
	v_mfma_f32_32x32x16_bf16 v[48:63], v[10:13], v[192:195], v[48:63]
	ds_read_b64_tr_b16 v[192:193], v14 offset:0x3600
	ds_read_b64_tr_b16 v[194:195], v14 offset:0x3e00
	s_waitcnt lgkmcnt(0)
	v_mfma_f32_32x32x16_bf16 v[32:47], v[6:9], v[148:151], v[32:47]
	s_and_b64 vcc, exec, s[0:1]
	v_mfma_f32_32x32x16_bf16 v[32:47], v[2:5], v[152:155], v[32:47]
	v_mfma_f32_32x32x16_bf16 v[32:47], v[144:147], v[156:159], v[32:47]
	v_mfma_f32_32x32x16_bf16 v[32:47], v[10:13], v[192:195], v[32:47]
	s_cbranch_vccnz .LBB0_724
	s_branch .Lmy_r2ft_1
.Lmy_r2d_2:
	s_mov_b32 s38, s36
	s_mov_b32 s39, s36
	s_mov_b32 s37, s36
	v_mov_b64_e32 v[118:119], s[38:39]
	v_mov_b64_e32 v[116:117], s[36:37]
	s_lshl_b32 s15, s18, 14
	v_add_u32_e32 v0, s15, v192
	v_mfma_f32_32x32x16_bf16 v[80:95], v[6:9], v[116:119], v[80:95]
	ds_read_b64_tr_b16 v[120:121], v0 offset:0
	ds_read_b64_tr_b16 v[122:123], v0 offset:0x800
	ds_read_b64_tr_b16 v[124:125], v0 offset:0x1000
	ds_read_b64_tr_b16 v[126:127], v0 offset:0x1800
	ds_read_b64_tr_b16 v[176:177], v0 offset:0x2000
	ds_read_b64_tr_b16 v[178:179], v0 offset:0x2800
	ds_read_b64_tr_b16 v[180:181], v0 offset:0x3000
	v_mfma_f32_32x32x16_bf16 v[80:95], v[2:5], v[116:119], v[80:95]
	global_load_lds_dwordx4 v[184:185], off
	v_lshl_add_u64 v[184:185], v[184:185], 0, s[74:75]
	ds_read_b64_tr_b16 v[182:183], v0 offset:0x3800
	s_waitcnt lgkmcnt(0)
	v_mfma_f32_32x32x16_bf16 v[80:95], v[112:115], v[116:119], v[80:95]
	v_mfma_f32_32x32x16_bf16 v[80:95], v[10:13], v[116:119], v[80:95]
	v_mfma_f32_32x32x16_bf16 v[64:79], v[6:9], v[120:123], v[64:79]
	ds_read_b64_tr_b16 v[116:117], v0 offset:0x200
	ds_read_b64_tr_b16 v[118:119], v0 offset:0xa00
	ds_read_b64_tr_b16 v[120:121], v0 offset:0x1200
	ds_read_b64_tr_b16 v[122:123], v0 offset:0x1a00
	v_mfma_f32_32x32x16_bf16 v[64:79], v[2:5], v[124:127], v[64:79]
	s_mov_b32 m0, s12
	s_nop 0
	global_load_lds_dwordx4 v[186:187], off
	v_lshl_add_u64 v[186:187], v[186:187], 0, s[74:75]
	ds_read_b64_tr_b16 v[124:125], v0 offset:0x2200
	ds_read_b64_tr_b16 v[126:127], v0 offset:0x2a00
	v_mfma_f32_32x32x16_bf16 v[64:79], v[112:115], v[176:179], v[64:79]
	ds_read_b64_tr_b16 v[176:177], v0 offset:0x3200
	ds_read_b64_tr_b16 v[178:179], v0 offset:0x3a00
	s_waitcnt lgkmcnt(0)
	v_mfma_f32_32x32x16_bf16 v[64:79], v[10:13], v[180:183], v[64:79]
	v_mfma_f32_32x32x16_bf16 v[48:63], v[6:9], v[116:119], v[48:63]
	ds_read_b64_tr_b16 v[116:117], v0 offset:0x400
	ds_read_b64_tr_b16 v[118:119], v0 offset:0xc00
	v_mfma_f32_32x32x16_bf16 v[48:63], v[2:5], v[120:123], v[48:63]
	s_add_i32 m0, s12, 0x2000
	s_nop 0
	global_load_lds_dwordx4 v[188:189], off
	v_lshl_add_u64 v[188:189], v[188:189], 0, s[74:75]
	ds_read_b64_tr_b16 v[120:121], v0 offset:0x1400
	ds_read_b64_tr_b16 v[122:123], v0 offset:0x1c00
	v_mfma_f32_32x32x16_bf16 v[48:63], v[112:115], v[124:127], v[48:63]
	ds_read_b64_tr_b16 v[124:125], v0 offset:0x2400
	ds_read_b64_tr_b16 v[126:127], v0 offset:0x2c00
	v_mfma_f32_32x32x16_bf16 v[48:63], v[10:13], v[176:179], v[48:63]
	ds_read_b64_tr_b16 v[176:177], v0 offset:0x3400
	ds_read_b64_tr_b16 v[178:179], v0 offset:0x3c00
	s_waitcnt lgkmcnt(0)
	v_mfma_f32_32x32x16_bf16 v[32:47], v[6:9], v[116:119], v[32:47]
	ds_read_b64_tr_b16 v[116:117], v0 offset:0x600
	ds_read_b64_tr_b16 v[118:119], v0 offset:0xe00
	v_mfma_f32_32x32x16_bf16 v[32:47], v[2:5], v[120:123], v[32:47]
	ds_read_b64_tr_b16 v[120:121], v0 offset:0x1600
	ds_read_b64_tr_b16 v[122:123], v0 offset:0x1e00
	v_mfma_f32_32x32x16_bf16 v[32:47], v[112:115], v[124:127], v[32:47]
	ds_read_b64_tr_b16 v[124:125], v0 offset:0x2600
	ds_read_b64_tr_b16 v[126:127], v0 offset:0x2e00
	v_mfma_f32_32x32x16_bf16 v[32:47], v[10:13], v[176:179], v[32:47]
	ds_read_b64_tr_b16 v[176:177], v0 offset:0x3600
	ds_read_b64_tr_b16 v[178:179], v0 offset:0x3e00
	s_waitcnt lgkmcnt(0)
	v_mfma_f32_32x32x16_bf16 v[16:31], v[6:9], v[116:119], v[16:31]
	s_and_b64 vcc, exec, s[0:1]
	v_mfma_f32_32x32x16_bf16 v[16:31], v[2:5], v[120:123], v[16:31]
	v_mfma_f32_32x32x16_bf16 v[16:31], v[112:115], v[124:127], v[16:31]
	v_mfma_f32_32x32x16_bf16 v[16:31], v[10:13], v[176:179], v[16:31]
	s_cbranch_vccnz .LBB0_784
	s_branch .Lmy_r2ft_2
; #define SBAR() __builtin_amdgcn_sched_barrier(0)
; template <int D0> __device__ __forceinline__ void pv_one(f32x16& od, int vb, bf16x8 pa0, bf16x8 pa1, bf16x8 pa2, bf16x8 pa3) {
;     const s16x4 l0 = tr_read<v_rd_off(D0, 0, 0)>(vb), h0 = tr_read<v_rd_off(D0, 0, 1)>(vb), l1 = tr_read<v_rd_off(D0, 1, 0)>(vb), h1 = tr_read<v_rd_off(D0, 1, 1)>(vb);
;     const s16x4 l2 = tr_read<v_rd_off(D0, 2, 0)>(vb), h2 = tr_read<v_rd_off(D0, 2, 1)>(vb), l3 = tr_read<v_rd_off(D0, 3, 0)>(vb), h3 = tr_read<v_rd_off(D0, 3, 1)>(vb);
;     asm volatile("s_waitcnt lgkmcnt(0)" ::: "memory"); SBAR();
;     ...
;     od = __builtin_amdgcn_mfma_f32_32x32x16_bf16(pa0, PK(l0, h0), od, 0, 0, 0);
;     od = __builtin_amdgcn_mfma_f32_32x32x16_bf16(pa1, PK(l1, h1), od, 0, 0, 0);
;     od = __builtin_amdgcn_mfma_f32_32x32x16_bf16(pa2, PK(l2, h2), od, 0, 0, 0);
;     od = __builtin_amdgcn_mfma_f32_32x32x16_bf16(pa3, PK(l3, h3), od, 0, 0, 0);
;     ...
; }
; template <bool RSM> __device__ __forceinline__ void pv_d0(f32x16* o, f32x16& lacc, int vb, bf16x8 pa0, bf16x8 pa1, bf16x8 pa2, bf16x8 pa3) {
;     if (RSM) {
;         const bf16x8 ones = {0x3F80, 0x3F80, 0x3F80, 0x3F80, 0x3F80, 0x3F80, 0x3F80, 0x3F80};
;         lacc = __builtin_amdgcn_mfma_f32_32x32x16_bf16(pa0, ones, lacc, 0, 0, 0);
;         lacc = __builtin_amdgcn_mfma_f32_32x32x16_bf16(pa1, ones, lacc, 0, 0, 0);
;         lacc = __builtin_amdgcn_mfma_f32_32x32x16_bf16(pa2, ones, lacc, 0, 0, 0);
;         lacc = __builtin_amdgcn_mfma_f32_32x32x16_bf16(pa3, ones, lacc, 0, 0, 0); }
;     pv_one<0>(o[0], vb, pa0, pa1, pa2, pa3); pv_one<1>(o[1], vb, pa0, pa1, pa2, pa3); pv_one<2>(o[2], vb, pa0, pa1, pa2, pa3); pv_one<3>(o[3], vb, pa0, pa1, pa2, pa3);
.Lmy_r2d_3:
	s_mov_b32 s38, s36
	s_mov_b32 s39, s36
	s_mov_b32 s37, s36
	v_mov_b64_e32 v[134:135], s[38:39]
	v_mov_b64_e32 v[132:133], s[36:37]
	s_lshl_b32 s31, s18, 14
	v_add_u32_e32 v14, s31, v192
	v_mfma_f32_32x32x16_bf16 v[80:95], v[6:9], v[132:135], v[80:95]
	ds_read_b64_tr_b16 v[136:137], v14 offset:0
	ds_read_b64_tr_b16 v[138:139], v14 offset:0x800
	ds_read_b64_tr_b16 v[140:141], v14 offset:0x1000
	ds_read_b64_tr_b16 v[142:143], v14 offset:0x1800
	ds_read_b64_tr_b16 v[176:177], v14 offset:0x2000
	ds_read_b64_tr_b16 v[178:179], v14 offset:0x2800
	ds_read_b64_tr_b16 v[180:181], v14 offset:0x3000
	v_mfma_f32_32x32x16_bf16 v[80:95], v[2:5], v[132:135], v[80:95]
	global_load_lds_dwordx4 v[184:185], off
	v_lshl_add_u64 v[184:185], v[184:185], 0, s[74:75]
	ds_read_b64_tr_b16 v[182:183], v14 offset:0x3800
	s_waitcnt lgkmcnt(0)
	v_mfma_f32_32x32x16_bf16 v[80:95], v[128:131], v[132:135], v[80:95]
	v_mfma_f32_32x32x16_bf16 v[80:95], v[10:13], v[132:135], v[80:95]
	v_mfma_f32_32x32x16_bf16 v[64:79], v[6:9], v[136:139], v[64:79]
	ds_read_b64_tr_b16 v[132:133], v14 offset:0x200
	ds_read_b64_tr_b16 v[134:135], v14 offset:0xa00
	ds_read_b64_tr_b16 v[136:137], v14 offset:0x1200
	ds_read_b64_tr_b16 v[138:139], v14 offset:0x1a00
	v_mfma_f32_32x32x16_bf16 v[64:79], v[2:5], v[140:143], v[64:79]
	s_mov_b32 m0, s14
	s_nop 0
	global_load_lds_dwordx4 v[186:187], off
	v_lshl_add_u64 v[186:187], v[186:187], 0, s[74:75]
	ds_read_b64_tr_b16 v[140:141], v14 offset:0x2200
	ds_read_b64_tr_b16 v[142:143], v14 offset:0x2a00
	v_mfma_f32_32x32x16_bf16 v[64:79], v[128:131], v[176:179], v[64:79]
	ds_read_b64_tr_b16 v[176:177], v14 offset:0x3200
	ds_read_b64_tr_b16 v[178:179], v14 offset:0x3a00
	s_waitcnt lgkmcnt(0)
	v_mfma_f32_32x32x16_bf16 v[64:79], v[10:13], v[180:183], v[64:79]
	v_mfma_f32_32x32x16_bf16 v[48:63], v[6:9], v[132:135], v[48:63]
	ds_read_b64_tr_b16 v[132:133], v14 offset:0x400
	ds_read_b64_tr_b16 v[134:135], v14 offset:0xc00
	v_mfma_f32_32x32x16_bf16 v[48:63], v[2:5], v[136:139], v[48:63]
	s_add_i32 m0, s14, 0x2000
	s_nop 0
	global_load_lds_dwordx4 v[188:189], off
	v_lshl_add_u64 v[188:189], v[188:189], 0, s[74:75]
	ds_read_b64_tr_b16 v[136:137], v14 offset:0x1400
	ds_read_b64_tr_b16 v[138:139], v14 offset:0x1c00
	v_mfma_f32_32x32x16_bf16 v[48:63], v[128:131], v[140:143], v[48:63]
	ds_read_b64_tr_b16 v[140:141], v14 offset:0x2400
	ds_read_b64_tr_b16 v[142:143], v14 offset:0x2c00
	v_mfma_f32_32x32x16_bf16 v[48:63], v[10:13], v[176:179], v[48:63]
	ds_read_b64_tr_b16 v[176:177], v14 offset:0x3400
	ds_read_b64_tr_b16 v[178:179], v14 offset:0x3c00
	s_waitcnt lgkmcnt(0)
	v_mfma_f32_32x32x16_bf16 v[32:47], v[6:9], v[132:135], v[32:47]
	ds_read_b64_tr_b16 v[132:133], v14 offset:0x600
	ds_read_b64_tr_b16 v[134:135], v14 offset:0xe00
	v_mfma_f32_32x32x16_bf16 v[32:47], v[2:5], v[136:139], v[32:47]
	ds_read_b64_tr_b16 v[136:137], v14 offset:0x1600
	ds_read_b64_tr_b16 v[138:139], v14 offset:0x1e00
	v_mfma_f32_32x32x16_bf16 v[32:47], v[128:131], v[140:143], v[32:47]
	ds_read_b64_tr_b16 v[140:141], v14 offset:0x2600
	ds_read_b64_tr_b16 v[142:143], v14 offset:0x2e00
	v_mfma_f32_32x32x16_bf16 v[32:47], v[10:13], v[176:179], v[32:47]
	ds_read_b64_tr_b16 v[176:177], v14 offset:0x3600
	ds_read_b64_tr_b16 v[178:179], v14 offset:0x3e00
	s_waitcnt lgkmcnt(0)
	v_mfma_f32_32x32x16_bf16 v[16:31], v[6:9], v[132:135], v[16:31]
	s_and_b64 vcc, exec, s[0:1]
	v_mfma_f32_32x32x16_bf16 v[16:31], v[2:5], v[136:139], v[16:31]
	v_mfma_f32_32x32x16_bf16 v[16:31], v[128:131], v[140:143], v[16:31]
	v_mfma_f32_32x32x16_bf16 v[16:31], v[10:13], v[176:179], v[16:31]
	s_cbranch_vccnz .LBB0_799
	s_branch .Lmy_r2ft_3

.LBB0_777:
	s_lshl_b32 s12, s18, 14
	s_add_i32 m0, s81, s14
	s_addk_i32 s12, 0xc000
	s_cmp_gt_i32 s18, 0
	s_cselect_b32 s12, s12, 0xc000
	s_waitcnt vmcnt(3) lgkmcnt(0)
	s_barrier
	s_add_i32 s12, s63, s12
	s_branch .Lmy_r2d_2

.Lmy_r2ft_2:
	s_cmpk_gt_u32 s17, 0xfc
	s_mov_b64 s[12:13], -1
	s_cbranch_scc1 .LBB0_821
	s_andn2_b64 vcc, exec, s[12:13]
	s_cbranch_vccnz .LBB0_783

.LBB0_792:
	s_lshl_b32 s14, s18, 14
	s_add_i32 m0, s81, s26
	s_addk_i32 s14, 0xc000
	s_cmp_gt_i32 s18, 0
	s_cselect_b32 s14, s14, 0xc000
	s_waitcnt vmcnt(3) lgkmcnt(0)
	s_barrier
	s_add_i32 s14, s63, s14
	s_branch .Lmy_r2d_3

.Lmy_r2ft_3:
	s_cmpk_gt_u32 s17, 0xfb
	s_mov_b64 s[14:15], -1
	s_cbranch_scc1 .LBB0_831
	s_andn2_b64 vcc, exec, s[14:15]
	s_cbranch_vccnz .LBB0_798
